# out-proj K-loop per-half copies: leading half waits at end of MFMA segments, trailing half issues every LDS-DMA group one barrier interval earlier inside the preceding MFMA segment (+1 interval latenc
# speedup vs baseline: 1.0042x; 1.0042x over previous
; #define PG8_STAGE(bufoff, gbase, voff) do { _Pragma("unroll") for (int _i = 0; _i < 2; ++_i) \
;         __builtin_amdgcn_global_load_lds((const unsigned*)((const char*)(gbase) + (voff)[_i]), (PG8_LAS unsigned*)(lds + (bufoff) + ldsw + _i * 8192), 16, 0, 0); } while (0)
; #define PG8_LDA(dst, b, h) do { _Pragma("unroll") for (int m = 0; m < 4; ++m) _Pragma("unroll") for (int k = 0; k < 2; ++k) dst[m][k] = *(const PG8_LAS bf16x8*)(lds + PG8_SA(b, h) + aoff + m * 2048 + k * 1024); } while (0)
; #define PG8_LDB(dst, b, h) do { _Pragma("unroll") for (int n = 0; n < 2; ++n) _Pragma("unroll") for (int k = 0; k < 2; ++k) dst[n][k] = *(const PG8_LAS bf16x8*)(lds + PG8_SB(b, h) + boff + n * 2048 + k * 1024); } while (0)
; #define PG8_WAIT_V(n) asm volatile("s_waitcnt vmcnt(" #n ")" ::: "memory")
; template <class Epi, class Sched, bool ALIGN_EPI = false, bool SP2 = false>
; __device__ __forceinline__ void gemm_phase(PG8_LAS unsigned char* lds, const Gemm g, const Sched& S, const Epi& E) {
;     ...
;         const char* nA = has_next ? (const char*)(nxt.sw ? g.A2 : g.A) + (size_t)nxt.pm * tstep : cA; const char* nB = has_next ? (const char*)(nxt.sw ? g.Bt2 : g.Bt) + (size_t)nxt.pn * tstep : cB;
;         for (int t = 0; t < nt; t += 2) {
;             if constexpr (Epi::PF_TRIPS > 0) { if (t == nt - 2 * Epi::PF_TRIPS) E.prefetch(cur, tid, lds + STAGE_BYTES + wid * 512); }
;             const bool last = (t == nt - 2);
;             const char* a1 = cA + (size_t)(t + 1) * kstep;
;             const char* a2 = last ? nA : cA + (size_t)(t + 2) * kstep; const char* b2 = last ? nB : cB + (size_t)(t + 2) * kstep;
;             const char* a3 = a2 + kstep; const char* b3 = b2 + kstep;
;             if (last && has_next) S.a_ready(nxt);
;             if constexpr (SP2) {
;             PG8_LDB(B0, 0, 0); PG8_LDB(B1, 0, 1); PG8_SCHED; PG8_LDA(At, 0, 0); PG8_STAGE(PG8_SA(1, 1), a1 + hstep, voffA);
;             PG8_WAIT_V(8); PG8_WAIT_L(0); PG8_BAR; PG8_MMA(0, 0, At, B0); PG8_MMA(0, 1, At, B1); PG8_BAR; PG8_SCHED;
;     ...
; #pragma unroll
;         for (int a = 0; a < 2; ++a)
; #pragma unroll
;             for (int b = 0; b < 2; ++b)
; #pragma unroll
;                 for (int m = 0; m < 4; ++m)
; #pragma unroll
;                     for (int n = 0; n < 2; ++n) acc[a][b][m][n] = (f32x4){0.f, 0.f, 0.f, 0.f};
;         cur = nxt; cA = nA; cB = nB; ++ui;
.LBB0_382:
	s_lshl_b32 s46, s46, 8
	s_ashr_i32 s47, s46, 31
	s_lshl_b32 s48, s20, 8
	s_ashr_i32 s49, s48, 31
	s_lshl_b64 s[50:51], s[46:47], 11
	s_add_u32 s47, s30, s50
	s_addc_u32 s52, s31, s51
	s_lshl_b64 s[50:51], s[48:49], 1
	s_add_u32 s50, s47, s50
	s_addc_u32 s51, s52, s51
	s_add_u32 s52, s50, 0x40000
	s_addc_u32 s53, s51, 0
	s_add_u32 s47, s54, 0x100
	s_addc_u32 s49, s55, 0
	s_add_u32 s54, s44, 0x80
	s_addc_u32 s55, s45, 0
	v_mov_b32_e32 v0, 0
	v_lshl_add_u64 v[130:131], s[54:55], 0, v[180:181]
	v_lshl_add_u64 v[132:133], s[54:55], 0, v[182:183]
	s_mov_b32 s56, 0
	s_mov_b64 s[54:55], 0
	s_waitcnt lgkmcnt(0)
	v_mov_b32_e32 v1, v0
	v_mov_b32_e32 v2, v0
	v_mov_b32_e32 v3, v0
	v_mov_b32_e32 v4, v0
	v_mov_b32_e32 v5, v0
	v_mov_b32_e32 v6, v0
	v_mov_b32_e32 v7, v0
	v_mov_b32_e32 v16, v0
	v_mov_b32_e32 v17, v0
	v_mov_b32_e32 v18, v0
	v_mov_b32_e32 v19, v0
	v_mov_b32_e32 v20, v0
	v_mov_b32_e32 v21, v0
	v_mov_b32_e32 v22, v0
	v_mov_b32_e32 v23, v0
	v_mov_b32_e32 v32, v0
	v_mov_b32_e32 v33, v0
	v_mov_b32_e32 v34, v0
	v_mov_b32_e32 v35, v0
	v_mov_b32_e32 v36, v0
	v_mov_b32_e32 v37, v0
	v_mov_b32_e32 v38, v0
	v_mov_b32_e32 v39, v0
	v_mov_b32_e32 v48, v0
	v_mov_b32_e32 v49, v0
	v_mov_b32_e32 v50, v0
	v_mov_b32_e32 v51, v0
	v_mov_b32_e32 v52, v0
	v_mov_b32_e32 v53, v0
	v_mov_b32_e32 v54, v0
	v_mov_b32_e32 v55, v0
	v_mov_b32_e32 v8, v0
	v_mov_b32_e32 v9, v0
	v_mov_b32_e32 v10, v0
	v_mov_b32_e32 v11, v0
	v_mov_b32_e32 v12, v0
	v_mov_b32_e32 v13, v0
	v_mov_b32_e32 v14, v0
	v_mov_b32_e32 v15, v0
	v_mov_b32_e32 v24, v0
	v_mov_b32_e32 v25, v0
	v_mov_b32_e32 v26, v0
	v_mov_b32_e32 v27, v0
	v_mov_b32_e32 v28, v0
	v_mov_b32_e32 v29, v0
	v_mov_b32_e32 v30, v0
	v_mov_b32_e32 v31, v0
	v_mov_b32_e32 v40, v0
	v_mov_b32_e32 v41, v0
	v_mov_b32_e32 v42, v0
	v_mov_b32_e32 v43, v0
	v_mov_b32_e32 v44, v0
	v_mov_b32_e32 v45, v0
	v_mov_b32_e32 v46, v0
	v_mov_b32_e32 v47, v0
	v_mov_b32_e32 v56, v0
	v_mov_b32_e32 v57, v0
	v_mov_b32_e32 v58, v0
	v_mov_b32_e32 v59, v0
	v_mov_b32_e32 v60, v0
	v_mov_b32_e32 v61, v0
	v_mov_b32_e32 v62, v0
	v_mov_b32_e32 v63, v0
	v_mov_b32_e32 v64, v0
	v_mov_b32_e32 v65, v0
	v_mov_b32_e32 v66, v0
	v_mov_b32_e32 v67, v0
	v_mov_b32_e32 v68, v0
	v_mov_b32_e32 v69, v0
	v_mov_b32_e32 v70, v0
	v_mov_b32_e32 v71, v0
	v_mov_b32_e32 v82, v0
	v_mov_b32_e32 v83, v0
	v_mov_b32_e32 v84, v0
	v_mov_b32_e32 v85, v0
	v_mov_b32_e32 v86, v0
	v_mov_b32_e32 v87, v0
	v_mov_b32_e32 v88, v0
	v_mov_b32_e32 v89, v0
	v_mov_b32_e32 v98, v0
	v_mov_b32_e32 v99, v0
	v_mov_b32_e32 v100, v0
	v_mov_b32_e32 v101, v0
	v_mov_b32_e32 v102, v0
	v_mov_b32_e32 v103, v0
	v_mov_b32_e32 v104, v0
	v_mov_b32_e32 v105, v0
	v_mov_b32_e32 v114, v0
	v_mov_b32_e32 v115, v0
	v_mov_b32_e32 v116, v0
	v_mov_b32_e32 v117, v0
	v_mov_b32_e32 v118, v0
	v_mov_b32_e32 v119, v0
	v_mov_b32_e32 v120, v0
	v_mov_b32_e32 v121, v0
	v_mov_b32_e32 v72, v0
	v_mov_b32_e32 v73, v0
	v_mov_b32_e32 v74, v0
	v_mov_b32_e32 v75, v0
	v_mov_b32_e32 v76, v0
	v_mov_b32_e32 v77, v0
	v_mov_b32_e32 v78, v0
	v_mov_b32_e32 v79, v0
	v_mov_b32_e32 v90, v0
	v_mov_b32_e32 v91, v0
	v_mov_b32_e32 v92, v0
	v_mov_b32_e32 v93, v0
	v_mov_b32_e32 v94, v0
	v_mov_b32_e32 v95, v0
	v_mov_b32_e32 v96, v0
	v_mov_b32_e32 v97, v0
	v_mov_b32_e32 v106, v0
	v_mov_b32_e32 v107, v0
	v_mov_b32_e32 v108, v0
	v_mov_b32_e32 v109, v0
	v_mov_b32_e32 v110, v0
	v_mov_b32_e32 v111, v0
	v_mov_b32_e32 v112, v0
	v_mov_b32_e32 v113, v0
	v_mov_b32_e32 v122, v0
	v_mov_b32_e32 v123, v0
	v_mov_b32_e32 v124, v0
	v_mov_b32_e32 v125, v0
	v_mov_b32_e32 v126, v0
	v_mov_b32_e32 v127, v0
	v_mov_b32_e32 v128, v0
	v_mov_b32_e32 v129, v0
	v_readfirstlane_b32 s100, v202
	s_nop 3
	s_lshr_b32 s100, s100, 8
	s_cmp_eq_u32 s100, 0
	s_cbranch_scc1 .Lop_A384
	s_cmp_lg_u32 s70, 1
	s_cbranch_scc1 .Lop_B384
	v_lshl_add_u64 v[246:247], v[130:131], 0, s[54:55]
	v_lshl_add_u64 v[252:253], v[132:133], 0, s[54:55]
	s_add_i32 m0, s58, 0xc000
	s_nop 0
	global_load_lds_dwordx4 v[246:247], off
	s_add_i32 m0, s58, 0xe000
	s_nop 0
	global_load_lds_dwordx4 v[252:253], off
	s_branch .Lop_B384

; #define PG8_STAGE(bufoff, gbase, voff) do { _Pragma("unroll") for (int _i = 0; _i < 2; ++_i) \
;         __builtin_amdgcn_global_load_lds((const unsigned*)((const char*)(gbase) + (voff)[_i]), (PG8_LAS unsigned*)(lds + (bufoff) + ldsw + _i * 8192), 16, 0, 0); } while (0)
; #define PG8_LDA(dst, b, h) do { _Pragma("unroll") for (int m = 0; m < 4; ++m) _Pragma("unroll") for (int k = 0; k < 2; ++k) dst[m][k] = *(const PG8_LAS bf16x8*)(lds + PG8_SA(b, h) + aoff + m * 2048 + k * 1024); } while (0)
; #define PG8_LDB(dst, b, h) do { _Pragma("unroll") for (int n = 0; n < 2; ++n) _Pragma("unroll") for (int k = 0; k < 2; ++k) dst[n][k] = *(const PG8_LAS bf16x8*)(lds + PG8_SB(b, h) + boff + n * 2048 + k * 1024); } while (0)
; #define PG8_MMA(ai, bj, At, Bt) do { __builtin_amdgcn_s_setprio(1); _Pragma("unroll") for (int m = 0; m < 4; ++m) _Pragma("unroll") for (int n = 0; n < 2; ++n) _Pragma("unroll") for (int k = 0; k < 2; ++k) \
;         acc[ai][bj][m][n] = __builtin_amdgcn_mfma_f32_16x16x32_bf16(Bt[n][k], At[m][k], acc[ai][bj][m][n], 0, 0, 0); __builtin_amdgcn_s_setprio(0); } while (0)
; #define PG8_WAIT_V(n) asm volatile("s_waitcnt vmcnt(" #n ")" ::: "memory")
; #define PG8_WAIT_L(n) asm volatile("s_waitcnt lgkmcnt(" #n ")" ::: "memory")
; template <class Epi, class Sched, bool ALIGN_EPI = false, bool SP2 = false>
; __device__ __forceinline__ void gemm_phase(PG8_LAS unsigned char* lds, const Gemm g, const Sched& S, const Epi& E) {
;     ...
;             const bool last = (t == nt - 2);
;             const char* a1 = cA + (size_t)(t + 1) * kstep;
;             const char* a2 = last ? nA : cA + (size_t)(t + 2) * kstep; const char* b2 = last ? nB : cB + (size_t)(t + 2) * kstep;
;             const char* a3 = a2 + kstep; const char* b3 = b2 + kstep;
;             if (last && has_next) S.a_ready(nxt);
;             if constexpr (SP2) {
;             PG8_LDB(B0, 0, 0); PG8_LDB(B1, 0, 1); PG8_SCHED; PG8_LDA(At, 0, 0); PG8_STAGE(PG8_SA(1, 1), a1 + hstep, voffA);
;             PG8_WAIT_V(8); PG8_WAIT_L(0); PG8_BAR; PG8_MMA(0, 0, At, B0); PG8_MMA(0, 1, At, B1); PG8_BAR; PG8_SCHED;
;             PG8_LDA(At, 0, 1); PG8_STAGE(PG8_SB(0, 0), b2, voffB); PG8_STAGE(PG8_SB(0, 1), b2 + hstep, voffB); PG8_STAGE(PG8_SA(0, 0), a2, voffA);
;             PG8_WAIT_V(8); PG8_WAIT_L(0); PG8_BAR; PG8_MMA(1, 0, At, B0); PG8_MMA(1, 1, At, B1); PG8_BAR; PG8_SCHED;
.Lop_B383:
	s_add_i32 s73, s56, 2
	s_add_u32 s57, s44, s54
	s_addc_u32 s74, s45, s55
	s_add_u32 s75, s57, 0x100
	s_addc_u32 s57, s74, 0
	s_add_u32 s74, s47, s54
	s_addc_u32 s76, s49, s55
	s_add_i32 s77, 0, 0x10000
	s_cmp_eq_u32 s15, s56
	s_cselect_b32 s57, s5, s57
	s_cselect_b32 s56, s4, s75
	s_cselect_b32 s75, s43, s76
	s_cselect_b32 s74, s42, s74
	s_cselect_b32 s100, 1, 0
	s_add_i32 s76, 0, 0x14000
	v_add_u32_e32 v146, s77, v209
	v_add_u32_e32 v188, s76, v209
	ds_read_b128 v[134:137], v146
	ds_read_b128 v[138:141], v146 offset:1024
	ds_read_b128 v[142:145], v146 offset:2048
	ds_read_b128 v[146:149], v146 offset:3072
	ds_read_b128 v[150:153], v188
	ds_read_b128 v[154:157], v188 offset:1024
	ds_read_b128 v[184:187], v188 offset:2048
	ds_read_b128 v[188:191], v188 offset:3072
	ds_read_b128 v[192:195], v211
	ds_read_b128 v[196:199], v211 offset:1024
	ds_read_b128 v[212:215], v211 offset:2048
	ds_read_b128 v[216:219], v211 offset:3072
	ds_read_b128 v[220:223], v211 offset:4096
	ds_read_b128 v[224:227], v211 offset:5120
	ds_read_b128 v[228:231], v211 offset:6144
	ds_read_b128 v[232:235], v211 offset:7168
	v_lshl_add_u64 v[200:201], s[74:75], 0, v[176:177]
	v_lshl_add_u64 v[236:237], s[74:75], 0, v[158:159]
	s_add_u32 s74, s74, s14
	s_addc_u32 s75, s75, 0
	v_lshl_add_u64 v[242:243], s[56:57], 0, v[178:179]
	v_lshl_add_u64 v[244:245], s[56:57], 0, v[160:161]
	v_lshl_add_u64 v[238:239], s[74:75], 0, v[176:177]
	v_lshl_add_u64 v[240:241], s[74:75], 0, v[158:159]
	s_waitcnt vmcnt(8)
	s_waitcnt lgkmcnt(0)
	s_setprio 1
	s_barrier
	v_mfma_f32_16x16x32_bf16 v[126:129], v[134:137], v[192:195], v[126:129]
	s_add_i32 m0, s39, 0x10000
	v_mfma_f32_16x16x32_bf16 v[122:125], v[142:145], v[192:195], v[122:125]
	global_load_lds_dwordx4 v[200:201], off
	v_mfma_f32_16x16x32_bf16 v[110:113], v[134:137], v[212:215], v[110:113]
	v_mfma_f32_16x16x32_bf16 v[106:109], v[142:145], v[212:215], v[106:109]
	s_add_i32 m0, s39, 0x12000
	v_mfma_f32_16x16x32_bf16 v[94:97], v[134:137], v[220:223], v[94:97]
	global_load_lds_dwordx4 v[236:237], off
	v_mfma_f32_16x16x32_bf16 v[90:93], v[142:145], v[220:223], v[90:93]
	v_mfma_f32_16x16x32_bf16 v[76:79], v[134:137], v[228:231], v[76:79]
	s_add_i32 m0, s39, 0x14000
	v_mfma_f32_16x16x32_bf16 v[72:75], v[142:145], v[228:231], v[72:75]
	global_load_lds_dwordx4 v[238:239], off
	v_mfma_f32_16x16x32_bf16 v[126:129], v[138:141], v[196:199], v[126:129]
	v_mfma_f32_16x16x32_bf16 v[122:125], v[146:149], v[196:199], v[122:125]
	s_add_i32 m0, s39, 0x16000
	v_mfma_f32_16x16x32_bf16 v[110:113], v[138:141], v[216:219], v[110:113]
	global_load_lds_dwordx4 v[240:241], off
	v_mfma_f32_16x16x32_bf16 v[106:109], v[146:149], v[216:219], v[106:109]
	v_mfma_f32_16x16x32_bf16 v[94:97], v[138:141], v[224:227], v[94:97]
	s_mov_b32 m0, s58
	v_mfma_f32_16x16x32_bf16 v[90:93], v[146:149], v[224:227], v[90:93]
	global_load_lds_dwordx4 v[242:243], off
	v_mfma_f32_16x16x32_bf16 v[76:79], v[138:141], v[232:235], v[76:79]
	v_mfma_f32_16x16x32_bf16 v[72:75], v[146:149], v[232:235], v[72:75]
	s_mov_b32 m0, s59
	v_mfma_f32_16x16x32_bf16 v[118:121], v[150:153], v[192:195], v[118:121]
	global_load_lds_dwordx4 v[244:245], off
	v_mfma_f32_16x16x32_bf16 v[114:117], v[184:187], v[192:195], v[114:117]
	v_mfma_f32_16x16x32_bf16 v[102:105], v[150:153], v[212:215], v[102:105]
	v_mfma_f32_16x16x32_bf16 v[98:101], v[184:187], v[212:215], v[98:101]
	v_mfma_f32_16x16x32_bf16 v[86:89], v[150:153], v[220:223], v[86:89]
	v_mfma_f32_16x16x32_bf16 v[82:85], v[184:187], v[220:223], v[82:85]
	v_mfma_f32_16x16x32_bf16 v[68:71], v[150:153], v[228:231], v[68:71]
	v_mfma_f32_16x16x32_bf16 v[64:67], v[184:187], v[228:231], v[64:67]
	v_mfma_f32_16x16x32_bf16 v[118:121], v[154:157], v[196:199], v[118:121]
	v_mfma_f32_16x16x32_bf16 v[114:117], v[188:191], v[196:199], v[114:117]
	v_mfma_f32_16x16x32_bf16 v[102:105], v[154:157], v[216:219], v[102:105]
	v_mfma_f32_16x16x32_bf16 v[98:101], v[188:191], v[216:219], v[98:101]
	v_mfma_f32_16x16x32_bf16 v[86:89], v[154:157], v[224:227], v[86:89]
	v_mfma_f32_16x16x32_bf16 v[82:85], v[188:191], v[224:227], v[82:85]
	v_mfma_f32_16x16x32_bf16 v[68:71], v[154:157], v[232:235], v[68:71]
	v_mfma_f32_16x16x32_bf16 v[64:67], v[188:191], v[232:235], v[64:67]
	s_setprio 0
	s_barrier
	ds_read_b128 v[192:195], v211 offset:16384
	ds_read_b128 v[196:199], v211 offset:17408
	ds_read_b128 v[212:215], v211 offset:18432
	ds_read_b128 v[216:219], v211 offset:19456
	ds_read_b128 v[220:223], v211 offset:20480
	ds_read_b128 v[224:227], v211 offset:21504
	ds_read_b128 v[228:231], v211 offset:22528
	ds_read_b128 v[232:235], v211 offset:23552
	s_add_u32 s56, s56, s14
	s_addc_u32 s57, s57, 0
	s_nop 0
	v_lshl_add_u64 v[246:247], s[56:57], 0, v[178:179]
	v_lshl_add_u64 v[252:253], s[56:57], 0, v[160:161]
	s_waitcnt vmcnt(8)
	s_waitcnt lgkmcnt(0)
	s_setprio 1
	s_barrier
; #define PG8_STAGE(bufoff, gbase, voff) do { _Pragma("unroll") for (int _i = 0; _i < 2; ++_i) \
;         __builtin_amdgcn_global_load_lds((const unsigned*)((const char*)(gbase) + (voff)[_i]), (PG8_LAS unsigned*)(lds + (bufoff) + ldsw + _i * 8192), 16, 0, 0); } while (0)
; #define PG8_LDA(dst, b, h) do { _Pragma("unroll") for (int m = 0; m < 4; ++m) _Pragma("unroll") for (int k = 0; k < 2; ++k) dst[m][k] = *(const PG8_LAS bf16x8*)(lds + PG8_SA(b, h) + aoff + m * 2048 + k * 1024); } while (0)
; #define PG8_LDB(dst, b, h) do { _Pragma("unroll") for (int n = 0; n < 2; ++n) _Pragma("unroll") for (int k = 0; k < 2; ++k) dst[n][k] = *(const PG8_LAS bf16x8*)(lds + PG8_SB(b, h) + boff + n * 2048 + k * 1024); } while (0)
; #define PG8_MMA(ai, bj, At, Bt) do { __builtin_amdgcn_s_setprio(1); _Pragma("unroll") for (int m = 0; m < 4; ++m) _Pragma("unroll") for (int n = 0; n < 2; ++n) _Pragma("unroll") for (int k = 0; k < 2; ++k) \
;         acc[ai][bj][m][n] = __builtin_amdgcn_mfma_f32_16x16x32_bf16(Bt[n][k], At[m][k], acc[ai][bj][m][n], 0, 0, 0); __builtin_amdgcn_s_setprio(0); } while (0)
; #define PG8_WAIT_V(n) asm volatile("s_waitcnt vmcnt(" #n ")" ::: "memory")
; #define PG8_WAIT_L(n) asm volatile("s_waitcnt lgkmcnt(" #n ")" ::: "memory")
; #define PG8_BAR __builtin_amdgcn_s_barrier()
; #define PG8_SCHED __builtin_amdgcn_sched_barrier(0)
; template <class Epi, class Sched, bool ALIGN_EPI = false, bool SP2 = false>
; __device__ __forceinline__ void gemm_phase(PG8_LAS unsigned char* lds, const Gemm g, const Sched& S, const Epi& E) {
;     ...
;             PG8_WAIT_V(8); PG8_WAIT_L(0); PG8_BAR; PG8_MMA(1, 0, At, B0); PG8_MMA(1, 1, At, B1); PG8_BAR; PG8_SCHED;
;             PG8_LDB(B0, 1, 0); PG8_LDB(B1, 1, 1); PG8_SCHED; PG8_LDA(At, 1, 0); PG8_STAGE(PG8_SA(0, 1), a2 + hstep, voffA);
;             PG8_WAIT_V(8); PG8_WAIT_L(0); PG8_BAR; PG8_MMA(0, 0, At, B0); PG8_MMA(0, 1, At, B1); PG8_BAR; PG8_SCHED;
;             PG8_LDA(At, 1, 1); PG8_STAGE(PG8_SB(1, 0), b3, voffB); PG8_STAGE(PG8_SB(1, 1), b3 + hstep, voffB); PG8_STAGE(PG8_SA(1, 0), a3, voffA);
	v_mfma_f32_16x16x32_bf16 v[60:63], v[134:137], v[192:195], v[60:63]
	s_mov_b32 m0, s60
	v_mfma_f32_16x16x32_bf16 v[56:59], v[142:145], v[192:195], v[56:59]
	global_load_lds_dwordx4 v[246:247], off
	v_mfma_f32_16x16x32_bf16 v[44:47], v[134:137], v[212:215], v[44:47]
	v_mfma_f32_16x16x32_bf16 v[40:43], v[142:145], v[212:215], v[40:43]
	s_mov_b32 m0, s61
	v_mfma_f32_16x16x32_bf16 v[28:31], v[134:137], v[220:223], v[28:31]
	global_load_lds_dwordx4 v[252:253], off
	v_mfma_f32_16x16x32_bf16 v[24:27], v[142:145], v[220:223], v[24:27]
	v_mfma_f32_16x16x32_bf16 v[12:15], v[134:137], v[228:231], v[12:15]
	v_mfma_f32_16x16x32_bf16 v[8:11], v[142:145], v[228:231], v[8:11]
	v_mfma_f32_16x16x32_bf16 v[60:63], v[138:141], v[196:199], v[60:63]
	v_mfma_f32_16x16x32_bf16 v[56:59], v[146:149], v[196:199], v[56:59]
	v_mfma_f32_16x16x32_bf16 v[44:47], v[138:141], v[216:219], v[44:47]
	v_mfma_f32_16x16x32_bf16 v[40:43], v[146:149], v[216:219], v[40:43]
	v_mfma_f32_16x16x32_bf16 v[28:31], v[138:141], v[224:227], v[28:31]
	v_mfma_f32_16x16x32_bf16 v[24:27], v[146:149], v[224:227], v[24:27]
	v_mfma_f32_16x16x32_bf16 v[12:15], v[138:141], v[232:235], v[12:15]
	v_mfma_f32_16x16x32_bf16 v[8:11], v[146:149], v[232:235], v[8:11]
	v_mfma_f32_16x16x32_bf16 v[52:55], v[150:153], v[192:195], v[52:55]
	v_mfma_f32_16x16x32_bf16 v[48:51], v[184:187], v[192:195], v[48:51]
	v_mfma_f32_16x16x32_bf16 v[36:39], v[150:153], v[212:215], v[36:39]
	v_mfma_f32_16x16x32_bf16 v[32:35], v[184:187], v[212:215], v[32:35]
	v_mfma_f32_16x16x32_bf16 v[20:23], v[150:153], v[220:223], v[20:23]
	v_mfma_f32_16x16x32_bf16 v[16:19], v[184:187], v[220:223], v[16:19]
	v_mfma_f32_16x16x32_bf16 v[4:7], v[150:153], v[228:231], v[4:7]
	v_mfma_f32_16x16x32_bf16 v[0:3], v[184:187], v[228:231], v[0:3]
	v_mfma_f32_16x16x32_bf16 v[52:55], v[154:157], v[196:199], v[52:55]
	v_mfma_f32_16x16x32_bf16 v[48:51], v[188:191], v[196:199], v[48:51]
	v_mfma_f32_16x16x32_bf16 v[36:39], v[154:157], v[216:219], v[36:39]
	v_mfma_f32_16x16x32_bf16 v[32:35], v[188:191], v[216:219], v[32:35]
	v_mfma_f32_16x16x32_bf16 v[20:23], v[154:157], v[224:227], v[20:23]
	v_mfma_f32_16x16x32_bf16 v[16:19], v[188:191], v[224:227], v[16:19]
	v_mfma_f32_16x16x32_bf16 v[4:7], v[154:157], v[232:235], v[4:7]
	v_mfma_f32_16x16x32_bf16 v[0:3], v[188:191], v[232:235], v[0:3]
	s_setprio 0
	s_barrier
	s_add_i32 s74, 0, 0x18000
	s_add_i32 s75, 0, 0x1c000
	v_add_u32_e32 v146, s74, v209
	v_add_u32_e32 v188, s75, v209
	ds_read_b128 v[134:137], v146
	ds_read_b128 v[138:141], v146 offset:1024
	ds_read_b128 v[142:145], v146 offset:2048
	ds_read_b128 v[146:149], v146 offset:3072
	ds_read_b128 v[150:153], v188
	ds_read_b128 v[154:157], v188 offset:1024
	ds_read_b128 v[184:187], v188 offset:2048
	ds_read_b128 v[188:191], v188 offset:3072
	ds_read_b128 v[192:195], v211 offset:32768
	ds_read_b128 v[196:199], v211 offset:33792
	ds_read_b128 v[212:215], v211 offset:34816
	ds_read_b128 v[216:219], v211 offset:35840
	ds_read_b128 v[220:223], v211 offset:36864
	ds_read_b128 v[224:227], v211 offset:37888
	ds_read_b128 v[228:231], v211 offset:38912
	ds_read_b128 v[232:235], v211 offset:39936
	v_lshl_add_u64 v[200:201], v[200:201], 0, s[40:41]
	v_lshl_add_u64 v[236:237], v[236:237], 0, s[40:41]
	v_lshl_add_u64 v[238:239], v[238:239], 0, s[40:41]
	v_lshl_add_u64 v[240:241], v[240:241], 0, s[40:41]
	v_lshl_add_u64 v[242:243], v[242:243], 0, s[40:41]
	v_lshl_add_u64 v[244:245], v[244:245], 0, s[40:41]
	s_waitcnt vmcnt(8)
	s_waitcnt lgkmcnt(0)
	s_setprio 1
	s_barrier
	v_mfma_f32_16x16x32_bf16 v[126:129], v[134:137], v[192:195], v[126:129]
	s_add_i32 m0, s39, 0x18000
	v_mfma_f32_16x16x32_bf16 v[122:125], v[142:145], v[192:195], v[122:125]
	global_load_lds_dwordx4 v[200:201], off
	v_mfma_f32_16x16x32_bf16 v[110:113], v[134:137], v[212:215], v[110:113]
	v_mfma_f32_16x16x32_bf16 v[106:109], v[142:145], v[212:215], v[106:109]
	s_add_i32 m0, s39, 0x1a000
	v_mfma_f32_16x16x32_bf16 v[94:97], v[134:137], v[220:223], v[94:97]
	global_load_lds_dwordx4 v[236:237], off
	v_mfma_f32_16x16x32_bf16 v[90:93], v[142:145], v[220:223], v[90:93]
	v_mfma_f32_16x16x32_bf16 v[76:79], v[134:137], v[228:231], v[76:79]
	s_add_i32 m0, s39, 0x1c000
	v_mfma_f32_16x16x32_bf16 v[72:75], v[142:145], v[228:231], v[72:75]
	global_load_lds_dwordx4 v[238:239], off
	v_mfma_f32_16x16x32_bf16 v[126:129], v[138:141], v[196:199], v[126:129]
	v_mfma_f32_16x16x32_bf16 v[122:125], v[146:149], v[196:199], v[122:125]
	s_add_i32 m0, s39, 0x1e000
	v_mfma_f32_16x16x32_bf16 v[110:113], v[138:141], v[216:219], v[110:113]
	global_load_lds_dwordx4 v[240:241], off
	v_mfma_f32_16x16x32_bf16 v[106:109], v[146:149], v[216:219], v[106:109]
	v_mfma_f32_16x16x32_bf16 v[94:97], v[138:141], v[224:227], v[94:97]
	s_mov_b32 m0, s66
	v_mfma_f32_16x16x32_bf16 v[90:93], v[146:149], v[224:227], v[90:93]
	global_load_lds_dwordx4 v[242:243], off
	v_mfma_f32_16x16x32_bf16 v[76:79], v[138:141], v[232:235], v[76:79]
	v_mfma_f32_16x16x32_bf16 v[72:75], v[146:149], v[232:235], v[72:75]
	s_mov_b32 m0, s67
	v_mfma_f32_16x16x32_bf16 v[118:121], v[150:153], v[192:195], v[118:121]
	global_load_lds_dwordx4 v[244:245], off
	v_mfma_f32_16x16x32_bf16 v[114:117], v[184:187], v[192:195], v[114:117]
	v_mfma_f32_16x16x32_bf16 v[102:105], v[150:153], v[212:215], v[102:105]
	v_mfma_f32_16x16x32_bf16 v[98:101], v[184:187], v[212:215], v[98:101]
	v_mfma_f32_16x16x32_bf16 v[86:89], v[150:153], v[220:223], v[86:89]
	v_mfma_f32_16x16x32_bf16 v[82:85], v[184:187], v[220:223], v[82:85]
	v_mfma_f32_16x16x32_bf16 v[68:71], v[150:153], v[228:231], v[68:71]
	v_mfma_f32_16x16x32_bf16 v[64:67], v[184:187], v[228:231], v[64:67]
	v_mfma_f32_16x16x32_bf16 v[118:121], v[154:157], v[196:199], v[118:121]
	v_mfma_f32_16x16x32_bf16 v[114:117], v[188:191], v[196:199], v[114:117]
	v_mfma_f32_16x16x32_bf16 v[102:105], v[154:157], v[216:219], v[102:105]
	v_mfma_f32_16x16x32_bf16 v[98:101], v[188:191], v[216:219], v[98:101]
	v_mfma_f32_16x16x32_bf16 v[86:89], v[154:157], v[224:227], v[86:89]
	v_mfma_f32_16x16x32_bf16 v[82:85], v[188:191], v[224:227], v[82:85]
	v_mfma_f32_16x16x32_bf16 v[68:71], v[154:157], v[232:235], v[68:71]
	v_mfma_f32_16x16x32_bf16 v[64:67], v[188:191], v[232:235], v[64:67]
	s_setprio 0
	s_barrier
	ds_read_b128 v[192:195], v211 offset:49152
	ds_read_b128 v[196:199], v211 offset:50176
	ds_read_b128 v[212:215], v211 offset:51200
	ds_read_b128 v[216:219], v211 offset:52224
	ds_read_b128 v[220:223], v211 offset:53248
	ds_read_b128 v[224:227], v211 offset:54272
	ds_read_b128 v[228:231], v211 offset:55296
	ds_read_b128 v[232:235], v211 offset:56320
	s_cmp_eq_u32 s100, 1
	s_cbranch_scc1 .Lop_B_last
	s_add_u32 s56, s54, 0x100
	s_addc_u32 s57, s55, 0
	s_nop 0
	v_lshl_add_u64 v[246:247], v[130:131], 0, s[56:57]
	v_lshl_add_u64 v[252:253], v[132:133], 0, s[56:57]
	s_branch .Lop_B_d1
; #define PG8_STAGE(bufoff, gbase, voff) do { _Pragma("unroll") for (int _i = 0; _i < 2; ++_i) \
;         __builtin_amdgcn_global_load_lds((const unsigned*)((const char*)(gbase) + (voff)[_i]), (PG8_LAS unsigned*)(lds + (bufoff) + ldsw + _i * 8192), 16, 0, 0); } while (0)
; #define PG8_LDA(dst, b, h) do { _Pragma("unroll") for (int m = 0; m < 4; ++m) _Pragma("unroll") for (int k = 0; k < 2; ++k) dst[m][k] = *(const PG8_LAS bf16x8*)(lds + PG8_SA(b, h) + aoff + m * 2048 + k * 1024); } while (0)
; #define PG8_LDB(dst, b, h) do { _Pragma("unroll") for (int n = 0; n < 2; ++n) _Pragma("unroll") for (int k = 0; k < 2; ++k) dst[n][k] = *(const PG8_LAS bf16x8*)(lds + PG8_SB(b, h) + boff + n * 2048 + k * 1024); } while (0)
; #define PG8_WAIT_V(n) asm volatile("s_waitcnt vmcnt(" #n ")" ::: "memory")
; template <class Epi, class Sched, bool ALIGN_EPI = false, bool SP2 = false>
; __device__ __forceinline__ void gemm_phase(PG8_LAS unsigned char* lds, const Gemm g, const Sched& S, const Epi& E) {
;     ...
;             const char* a1 = cA + (size_t)(t + 1) * kstep;
;             const char* a2 = last ? nA : cA + (size_t)(t + 2) * kstep; const char* b2 = last ? nB : cB + (size_t)(t + 2) * kstep;
;             const char* a3 = a2 + kstep; const char* b3 = b2 + kstep;
;             if (last && has_next) S.a_ready(nxt);
;             if constexpr (SP2) {
;             PG8_LDB(B0, 0, 0); PG8_LDB(B1, 0, 1); PG8_SCHED; PG8_LDA(At, 0, 0); PG8_STAGE(PG8_SA(1, 1), a1 + hstep, voffA);
;             PG8_WAIT_V(8); PG8_WAIT_L(0); PG8_BAR; PG8_MMA(0, 0, At, B0); PG8_MMA(0, 1, At, B1); PG8_BAR; PG8_SCHED;
;             PG8_LDA(At, 0, 1); PG8_STAGE(PG8_SB(0, 0), b2, voffB); PG8_STAGE(PG8_SB(0, 1), b2 + hstep, voffB); PG8_STAGE(PG8_SA(0, 0), a2, voffA);
;             PG8_WAIT_V(8); PG8_WAIT_L(0); PG8_BAR; PG8_MMA(1, 0, At, B0); PG8_MMA(1, 1, At, B1); PG8_BAR; PG8_SCHED;
;             PG8_LDB(B0, 1, 0); PG8_LDB(B1, 1, 1); PG8_SCHED; PG8_LDA(At, 1, 0); PG8_STAGE(PG8_SA(0, 1), a2 + hstep, voffA);
;             PG8_WAIT_V(8); PG8_WAIT_L(0); PG8_BAR; PG8_MMA(0, 0, At, B0); PG8_MMA(0, 1, At, B1); PG8_BAR; PG8_SCHED;
;             PG8_LDA(At, 1, 1); PG8_STAGE(PG8_SB(1, 0), b3, voffB); PG8_STAGE(PG8_SB(1, 1), b3 + hstep, voffB); PG8_STAGE(PG8_SA(1, 0), a3, voffA);
;             PG8_WAIT_V(8); PG8_WAIT_L(0); PG8_BAR; PG8_MMA(1, 0, At, B0); PG8_MMA(1, 1, At, B1); PG8_BAR; PG8_SCHED;
.Lop_B_last:
	s_add_u32 s56, s4, 0x80
	s_addc_u32 s57, s5, 0
	s_nop 0
	v_lshl_add_u64 v[246:247], s[56:57], 0, v[180:181]
	v_lshl_add_u64 v[252:253], s[56:57], 0, v[182:183]
.Lop_B_d1:
	s_waitcnt vmcnt(8)
	s_waitcnt lgkmcnt(0)
	s_setprio 1
	s_barrier
	v_mfma_f32_16x16x32_bf16 v[60:63], v[134:137], v[192:195], v[60:63]
	s_add_i32 m0, s58, 0xc000
	v_mfma_f32_16x16x32_bf16 v[56:59], v[142:145], v[192:195], v[56:59]
	global_load_lds_dwordx4 v[246:247], off
	v_mfma_f32_16x16x32_bf16 v[44:47], v[134:137], v[212:215], v[44:47]
	v_mfma_f32_16x16x32_bf16 v[40:43], v[142:145], v[212:215], v[40:43]
	s_add_i32 m0, s58, 0xe000
	v_mfma_f32_16x16x32_bf16 v[28:31], v[134:137], v[220:223], v[28:31]
	global_load_lds_dwordx4 v[252:253], off
	v_mfma_f32_16x16x32_bf16 v[24:27], v[142:145], v[220:223], v[24:27]
	v_mfma_f32_16x16x32_bf16 v[12:15], v[134:137], v[228:231], v[12:15]
	v_mfma_f32_16x16x32_bf16 v[8:11], v[142:145], v[228:231], v[8:11]
	v_mfma_f32_16x16x32_bf16 v[60:63], v[138:141], v[196:199], v[60:63]
	v_mfma_f32_16x16x32_bf16 v[56:59], v[146:149], v[196:199], v[56:59]
	v_mfma_f32_16x16x32_bf16 v[44:47], v[138:141], v[216:219], v[44:47]
	v_mfma_f32_16x16x32_bf16 v[40:43], v[146:149], v[216:219], v[40:43]
	v_mfma_f32_16x16x32_bf16 v[28:31], v[138:141], v[224:227], v[28:31]
	v_mfma_f32_16x16x32_bf16 v[24:27], v[146:149], v[224:227], v[24:27]
	v_mfma_f32_16x16x32_bf16 v[12:15], v[138:141], v[232:235], v[12:15]
	v_mfma_f32_16x16x32_bf16 v[8:11], v[146:149], v[232:235], v[8:11]
	v_mfma_f32_16x16x32_bf16 v[52:55], v[150:153], v[192:195], v[52:55]
	v_mfma_f32_16x16x32_bf16 v[48:51], v[184:187], v[192:195], v[48:51]
	v_mfma_f32_16x16x32_bf16 v[36:39], v[150:153], v[212:215], v[36:39]
	v_mfma_f32_16x16x32_bf16 v[32:35], v[184:187], v[212:215], v[32:35]
	v_mfma_f32_16x16x32_bf16 v[20:23], v[150:153], v[220:223], v[20:23]
	v_mfma_f32_16x16x32_bf16 v[16:19], v[184:187], v[220:223], v[16:19]
	v_mfma_f32_16x16x32_bf16 v[4:7], v[150:153], v[228:231], v[4:7]
	v_mfma_f32_16x16x32_bf16 v[0:3], v[184:187], v[228:231], v[0:3]
	v_mfma_f32_16x16x32_bf16 v[52:55], v[154:157], v[196:199], v[52:55]
	v_mfma_f32_16x16x32_bf16 v[48:51], v[188:191], v[196:199], v[48:51]
	v_mfma_f32_16x16x32_bf16 v[36:39], v[154:157], v[216:219], v[36:39]
	v_mfma_f32_16x16x32_bf16 v[32:35], v[188:191], v[216:219], v[32:35]
	v_mfma_f32_16x16x32_bf16 v[20:23], v[154:157], v[224:227], v[20:23]
	v_mfma_f32_16x16x32_bf16 v[16:19], v[188:191], v[224:227], v[16:19]
	v_mfma_f32_16x16x32_bf16 v[4:7], v[154:157], v[232:235], v[4:7]
	v_mfma_f32_16x16x32_bf16 v[0:3], v[188:191], v[232:235], v[0:3]
	s_setprio 0
	s_barrier
	s_add_u32 s54, s54, 0x100
	s_addc_u32 s55, s55, 0
	s_cmp_ge_u32 s73, s63
	s_mov_b32 s56, s73
	s_cbranch_scc1 .LBB0_386

; __global__ void __launch_bounds__(NTHREADS, 2) fwd_megakernel(Params P) {
	.amdhsa_kernel _Z14fwd_megakernel6Params
		.amdhsa_group_segment_fixed_size 0
		.amdhsa_private_segment_fixed_size 0
		.amdhsa_kernarg_size 400
		.amdhsa_user_sgpr_count 2
		.amdhsa_user_sgpr_dispatch_ptr 0
		.amdhsa_user_sgpr_queue_ptr 0
		.amdhsa_user_sgpr_kernarg_segment_ptr 1
		.amdhsa_user_sgpr_dispatch_id 0
		.amdhsa_user_sgpr_kernarg_preload_length 0
		.amdhsa_user_sgpr_kernarg_preload_offset 0
		.amdhsa_user_sgpr_private_segment_size 0
		.amdhsa_uses_dynamic_stack 0
		.amdhsa_enable_private_segment 0
		.amdhsa_system_sgpr_workgroup_id_x 1
		.amdhsa_system_sgpr_workgroup_id_y 0
		.amdhsa_system_sgpr_workgroup_id_z 0
		.amdhsa_system_sgpr_workgroup_info 0
		.amdhsa_system_vgpr_workitem_id 2
		.amdhsa_next_free_vgpr 254
		.amdhsa_next_free_sgpr 102
		.amdhsa_accum_offset 256
		.amdhsa_reserve_vcc 1
		.amdhsa_float_round_mode_32 0
		.amdhsa_float_round_mode_16_64 0
		.amdhsa_float_denorm_mode_32 3
		.amdhsa_float_denorm_mode_16_64 3
		.amdhsa_dx10_clamp 1
		.amdhsa_ieee_mode 1
		.amdhsa_fp16_overflow 0
		.amdhsa_tg_split 0
		.amdhsa_exception_fp_ieee_invalid_op 0
		.amdhsa_exception_fp_denorm_src 0
		.amdhsa_exception_fp_ieee_div_zero 0
		.amdhsa_exception_fp_ieee_overflow 0
		.amdhsa_exception_fp_ieee_underflow 0
		.amdhsa_exception_fp_ieee_inexact 0
		.amdhsa_exception_int_div_zero 0
	.end_amdhsa_kernel

; __global__ void __launch_bounds__(NTHREADS, 2) fwd_megakernel(Params P) {
amdhsa.kernels:
  - .agpr_count:     0
    .args:
      - .offset:         0
        .size:           144
        .value_kind:     by_value
      - .offset:         144
        .size:           4
        .value_kind:     hidden_block_count_x
      - .offset:         148
        .size:           4
        .value_kind:     hidden_block_count_y
      - .offset:         152
        .size:           4
        .value_kind:     hidden_block_count_z
      - .offset:         156
        .size:           2
        .value_kind:     hidden_group_size_x
      - .offset:         158
        .size:           2
        .value_kind:     hidden_group_size_y
      - .offset:         160
        .size:           2
        .value_kind:     hidden_group_size_z
      - .offset:         162
        .size:           2
        .value_kind:     hidden_remainder_x
      - .offset:         164
        .size:           2
        .value_kind:     hidden_remainder_y
      - .offset:         166
        .size:           2
        .value_kind:     hidden_remainder_z
      - .offset:         184
        .size:           8
        .value_kind:     hidden_global_offset_x
      - .offset:         192
        .size:           8
        .value_kind:     hidden_global_offset_y
      - .offset:         200
        .size:           8
        .value_kind:     hidden_global_offset_z
      - .offset:         208
        .size:           2
        .value_kind:     hidden_grid_dims
      - .offset:         232
        .size:           8
        .value_kind:     hidden_multigrid_sync_arg
      - .offset:         264
        .size:           4
        .value_kind:     hidden_dynamic_lds_size
    .group_segment_fixed_size: 0
    .kernarg_segment_align: 8
    .kernarg_segment_size: 400
    .language:       OpenCL C
    .language_version:
      - 2
      - 0
    .max_flat_workgroup_size: 512
    .name:           _Z14fwd_megakernel6Params
    .private_segment_fixed_size: 0
    .sgpr_count:     108
    .sgpr_spill_count: 188
    .symbol:         _Z14fwd_megakernel6Params.kd
    .uniform_work_group_size: 1
    .uses_dynamic_stack: false
    .vgpr_count:     254
    .vgpr_spill_count: 0
    .wavefront_size: 64
